# gmlp/pool items remapped to be XCD-local (guarded by placement flag) making the local G1->M1 barrier race-free; P0 prep loop prefetches next row
# speedup vs baseline: 1.0408x; 1.0002x over previous
.LBB0_15:
	v_mov_b32_e32 v4, v214
	s_cmpk_lt_i32 s8, 0x4000
	s_barrier
	s_cbranch_scc0 .LBB0_20
	v_mbcnt_lo_u32_b32 v1, -1, 0
	v_mbcnt_hi_u32_b32 v2, -1, v1
	v_and_b32_e32 v1, 64, v2
	v_add_u32_e32 v3, 64, v1
	v_xor_b32_e32 v1, 1, v2
	v_cmp_lt_i32_e32 vcc, v1, v3
	v_xor_b32_e32 v6, 2, v2
	v_xor_b32_e32 v7, 4, v2
	v_cndmask_b32_e32 v1, v2, v1, vcc
	v_cmp_lt_i32_e32 vcc, v6, v3
	v_xor_b32_e32 v8, 8, v2
	v_xor_b32_e32 v9, 16, v2
	v_cndmask_b32_e32 v6, v2, v6, vcc
	v_cmp_lt_i32_e32 vcc, v7, v3
	s_ashr_i32 s9, s8, 31
	s_load_dwordx2 s[14:15], s[4:5], 0x0
	s_load_dwordx2 s[16:17], s[4:5], 0xd8
	v_cndmask_b32_e32 v7, v2, v7, vcc
	v_cmp_lt_i32_e32 vcc, v8, v3
	v_xor_b32_e32 v10, 32, v2
	s_lshl_b64 s[4:5], s[8:9], 4
	v_cndmask_b32_e32 v8, v2, v8, vcc
	v_cmp_lt_i32_e32 vcc, v9, v3
	s_add_u32 s12, s4, 0x10000
	v_ashrrev_i32_e32 v5, 31, v4
	v_cndmask_b32_e32 v9, v2, v9, vcc
	v_cmp_lt_i32_e32 vcc, v10, v3
	s_addc_u32 s13, s5, 0
	s_ashr_i32 s11, s10, 31
	v_cndmask_b32_e32 v2, v2, v10, vcc
	s_lshl_b64 s[4:5], s[8:9], 11
	v_lshlrev_b32_e32 v10, 2, v2
	s_lshl_b64 s[18:19], s[10:11], 4
	v_lshl_add_u64 v[2:3], v[4:5], 3, s[4:5]
	s_lshl_b64 s[20:21], s[10:11], 11
	s_lshl_b64 s[4:5], s[8:9], 12
	s_waitcnt lgkmcnt(0)
	s_add_u32 s4, s14, s4
	s_addc_u32 s5, s15, s5
	v_cmp_eq_u32_e32 vcc, 0, v4
	v_lshl_add_u64 v[4:5], v[4:5], 4, s[4:5]
	s_mov_b64 s[4:5], 0xc00
	v_lshlrev_b32_e32 v1, 2, v1
	v_lshlrev_b32_e32 v6, 2, v6
	v_lshlrev_b32_e32 v7, 2, v7
	v_lshlrev_b32_e32 v8, 2, v8
	v_lshlrev_b32_e32 v9, 2, v9
	v_lshl_add_u64 v[4:5], v[4:5], 0, s[4:5]
	s_lshl_b64 s[22:23], s[10:11], 12
	s_movk_i32 s9, 0x7fff
	s_mov_b32 s11, 0xffff0000
	s_mov_b32 s14, 0x3200000
	v_mov_b32_e32 v11, 0
	global_load_dwordx4 v[60:63], v[4:5], off offset:-3072
	global_load_dwordx4 v[64:67], v[4:5], off offset:-2048
	global_load_dwordx4 v[68:71], v[4:5], off offset:-1024
	global_load_dwordx4 v[72:75], v[4:5], off
	s_waitcnt vmcnt(0)
	v_mov_b64_e32 v[12:13], v[60:61]
	v_mov_b64_e32 v[14:15], v[62:63]
	v_mov_b64_e32 v[16:17], v[64:65]
	v_mov_b64_e32 v[18:19], v[66:67]
	v_mov_b64_e32 v[20:21], v[68:69]
	v_mov_b64_e32 v[22:23], v[70:71]
	v_mov_b64_e32 v[24:25], v[72:73]
	v_mov_b64_e32 v[26:27], v[74:75]
	s_branch .LBB0_18
.LBB0_17:
	s_or_b64 exec, exec, s[4:5]
	s_add_i32 s8, s8, s10
	s_add_u32 s12, s12, s18
	s_addc_u32 s13, s13, s19
	v_lshl_add_u64 v[2:3], v[2:3], 0, s[20:21]
	s_cmpk_gt_i32 s8, 0x3fff
	v_lshl_add_u64 v[4:5], v[4:5], 0, s[22:23]
	s_cbranch_scc1 .LBB0_20
	s_waitcnt vmcnt(5)
	v_mov_b64_e32 v[12:13], v[60:61]
	v_mov_b64_e32 v[14:15], v[62:63]
	v_mov_b64_e32 v[16:17], v[64:65]
	v_mov_b64_e32 v[18:19], v[66:67]
	v_mov_b64_e32 v[20:21], v[68:69]
	v_mov_b64_e32 v[22:23], v[70:71]
	v_mov_b64_e32 v[24:25], v[72:73]
	v_mov_b64_e32 v[26:27], v[74:75]
.LBB0_18:
	s_waitcnt lgkmcnt(0)
	s_add_i32 s74, s8, s10
	s_cmpk_gt_i32 s74, 0x3fff
	s_cbranch_scc1 .Lprep_nopf
	v_lshl_add_u64 v[76:77], v[4:5], 0, s[22:23]
	global_load_dwordx4 v[60:63], v[76:77], off offset:-3072
	global_load_dwordx4 v[64:67], v[76:77], off offset:-2048
	global_load_dwordx4 v[68:71], v[76:77], off offset:-1024
	global_load_dwordx4 v[72:75], v[76:77], off
.Lprep_nopf:
	v_lshl_add_u64 v[28:29], s[16:17], 0, v[2:3]
	v_add_co_u32_e64 v28, s[4:5], s14, v28
	v_mul_f32_e32 v30, v13, v13
	v_mul_f32_e32 v31, v15, v15
	v_mul_f32_e32 v32, v17, v17
	v_mul_f32_e32 v33, v19, v19
	v_mul_f32_e32 v34, v21, v21
	v_mul_f32_e32 v35, v23, v23
	v_fmac_f32_e32 v30, v12, v12
	v_fmac_f32_e32 v31, v14, v14
	v_fmac_f32_e32 v32, v16, v16
	v_fmac_f32_e32 v33, v18, v18
	v_mul_f32_e32 v36, v25, v25
	v_mul_f32_e32 v37, v27, v27
	v_fmac_f32_e32 v34, v20, v20
	v_fmac_f32_e32 v35, v22, v22
	v_add_f32_e32 v30, v30, v31
	v_add_f32_e32 v31, v32, v33
	v_fmac_f32_e32 v36, v24, v24
	v_fmac_f32_e32 v37, v26, v26
	v_add_f32_e32 v32, v34, v35
	v_add_f32_e32 v30, v30, v31
	v_add_f32_e32 v33, v36, v37
	v_add_f32_e32 v30, v30, v32
	v_add_f32_e32 v30, v30, v33
	ds_bpermute_b32 v31, v1, v30
	v_bfe_u32 v38, v12, 16, 1
	v_bfe_u32 v40, v14, 16, 1
	v_bfe_u32 v44, v18, 16, 1
	v_bfe_u32 v39, v13, 16, 1
	s_waitcnt lgkmcnt(0)
	v_add_f32_e32 v30, v30, v31
	ds_bpermute_b32 v31, v6, v30
	v_bfe_u32 v41, v15, 16, 1
	v_bfe_u32 v42, v16, 16, 1
	v_bfe_u32 v45, v19, 16, 1
	v_bfe_u32 v46, v20, 16, 1
	s_waitcnt lgkmcnt(0)
	v_add_f32_e32 v30, v30, v31
	ds_bpermute_b32 v31, v7, v30
	v_add3_u32 v12, v12, v38, s9
	v_add3_u32 v14, v14, v40, s9
	v_add3_u32 v18, v18, v44, s9
	v_bfe_u32 v43, v17, 16, 1
	s_waitcnt lgkmcnt(0)
	v_add_f32_e32 v30, v30, v31
	ds_bpermute_b32 v31, v8, v30
	v_bfe_u32 v47, v21, 16, 1
	v_add3_u32 v13, v13, v39, s9
	v_add3_u32 v15, v15, v41, s9
	v_add3_u32 v16, v16, v42, s9
	v_add3_u32 v19, v19, v45, s9
	v_add3_u32 v20, v20, v46, s9
	v_lshrrev_b32_e32 v12, 16, v12
	v_lshrrev_b32_e32 v14, 16, v14
	v_lshrrev_b32_e32 v18, 16, v18
	v_add3_u32 v17, v17, v43, s9
	v_add3_u32 v21, v21, v47, s9
	v_lshrrev_b32_e32 v16, 16, v16
	v_lshrrev_b32_e32 v20, 16, v20
	v_and_or_b32 v12, v13, s11, v12
	v_and_or_b32 v13, v15, s11, v14
	v_and_or_b32 v15, v19, s11, v18
	s_waitcnt lgkmcnt(0)
	v_add_f32_e32 v19, v30, v31
	v_and_or_b32 v14, v17, s11, v16
	v_and_or_b32 v16, v21, s11, v20
	ds_bpermute_b32 v20, v9, v19
	v_bfe_u32 v48, v22, 16, 1
	v_bfe_u32 v49, v23, 16, 1
	v_add3_u32 v22, v22, v48, s9
	v_addc_co_u32_e64 v29, s[4:5], 0, v29, s[4:5]
	v_add3_u32 v23, v23, v49, s9
	v_lshrrev_b32_e32 v22, 16, v22
	v_and_or_b32 v17, v23, s11, v22
	global_store_dwordx2 v[28:29], v[12:13], off
	global_store_dwordx2 v[28:29], v[14:15], off offset:512
	global_store_dwordx2 v[28:29], v[16:17], off offset:1024
	s_waitcnt lgkmcnt(0)
	v_add_f32_e32 v12, v19, v20
	ds_bpermute_b32 v13, v10, v12
	v_bfe_u32 v50, v24, 16, 1
	v_bfe_u32 v52, v26, 16, 1
	v_bfe_u32 v51, v25, 16, 1
	v_add3_u32 v24, v24, v50, s9
	v_add3_u32 v26, v26, v52, s9
	v_bfe_u32 v15, v27, 16, 1
	v_add3_u32 v25, v25, v51, s9
	v_lshrrev_b32_e32 v24, 16, v24
	v_lshrrev_b32_e32 v14, 16, v26
	v_add3_u32 v15, v27, v15, s9
	v_and_or_b32 v18, v25, s11, v24
	v_and_or_b32 v19, v15, s11, v14
	global_store_dwordx2 v[28:29], v[18:19], off offset:1536
	s_and_saveexec_b64 s[4:5], vcc
	s_cbranch_execz .LBB0_17
	s_add_u32 s24, s16, s12
	s_addc_u32 s25, s17, s13
	s_waitcnt lgkmcnt(0)
	v_add_f32_e32 v12, v12, v13
	global_store_dword v11, v12, s[24:25]
	s_branch .LBB0_17

.LBB0_350:
	v_readlane_b32 s0, v253, 39
	v_readlane_b32 s1, v253, 40
	s_andn2_b64 vcc, exec, s[0:1]
	v_readlane_b32 s26, v255, 18
	v_readlane_b32 s27, v255, 19
	s_cbranch_vccnz .LBB0_397
	s_lshl_b32 s22, s26, 8
	s_mov_b32 s23, s35
	s_lshl_b32 s11, s26, 9
	v_readlane_b32 s14, v252, 6
	v_readlane_b32 s74, v252, 5
	v_readlane_b32 s75, v255, 62
	s_nop 3
	s_and_b32 s74, s74, 7
	s_lshl_b32 s74, s74, 5
	s_cmp_lg_u32 s75, 0
	s_cselect_b32 s74, s74, 0
	s_add_i32 s14, s14, s74
	s_branch .LBB0_353

.LBB0_353:
	v_readlane_b32 s0, v252, 4
	v_readlane_b32 s75, v255, 62
	s_nop 3
	s_cmp_lg_u32 s75, 0
	s_cselect_b32 s75, 32, s0
	s_add_i32 s8, s14, s75
	s_lshl_b32 s9, s14, 5
	s_cmpk_gt_i32 s8, 0x1ff
	s_mov_b64 s[0:1], -1
	s_cbranch_scc0 .LBB0_357
	v_mov_b32_e32 v1, v214
	v_mov_b32_e32 v6, v0
	s_load_dwordx2 s[0:1], s[94:95], 0xd8
	s_load_dwordx4 s[44:47], s[94:95], 0x18
	s_and_b32 s19, s14, 3
	s_or_b32 s15, s19, s10
	s_lshl_b32 s34, s15, 14
	s_lshl_b64 s[4:5], s[34:35], 2
	v_lshlrev_b32_e32 v2, 2, v6
	s_waitcnt lgkmcnt(0)
	s_add_u32 s4, s46, s4
	v_and_b32_e32 v9, 0x7c, v2
	v_ashrrev_i32_e32 v14, 5, v6
	s_addc_u32 s5, s47, s5
	v_lshlrev_b32_e32 v2, 2, v9
	v_lshlrev_b32_e32 v10, 7, v14
	v_lshl_add_u64 v[4:5], s[4:5], 0, v[2:3]
	v_ashrrev_i32_e32 v11, 31, v10
	v_lshl_add_u64 v[10:11], v[10:11], 2, v[4:5]
	global_load_dwordx4 v[10:13], v[10:11], off
	v_cmp_le_i32_e64 s[4:5], v9, v14
	v_cmp_lt_i32_e32 vcc, v9, v14
	v_or_b32_e32 v8, 2, v9
	v_or_b32_e32 v7, 3, v9
	v_lshl_add_u32 v2, v9, 1, 0
	s_movk_i32 s6, 0x110
	s_mov_b32 s18, 0
	s_waitcnt vmcnt(0)
	v_cndmask_b32_e64 v10, 0, v10, s[4:5]
	v_bfe_u32 v15, v10, 16, 1
	v_cndmask_b32_e32 v11, 0, v11, vcc
	v_add3_u32 v10, v10, v15, s20
	v_bfe_u32 v15, v11, 16, 1
	v_lshrrev_b32_e32 v10, 16, v10
	v_add3_u32 v11, v11, v15, s20
	v_cmp_le_i32_e32 vcc, v8, v14
	v_and_or_b32 v10, v11, s33, v10
	s_nop 0
	v_cndmask_b32_e32 v11, 0, v12, vcc
	v_bfe_u32 v12, v11, 16, 1
	v_cmp_le_i32_e32 vcc, v7, v14
	v_add3_u32 v11, v11, v12, s20
	v_lshrrev_b32_e32 v11, 16, v11
	v_cndmask_b32_e32 v12, 0, v13, vcc
	v_bfe_u32 v13, v12, 16, 1
	v_add3_u32 v12, v12, v13, s20
	v_and_or_b32 v11, v12, s33, v11
	v_mad_u64_u32 v[12:13], s[4:5], v14, s6, v[2:3]
	ds_write_b64 v12, v[10:11]
	v_add_u32_e32 v10, 0x200, v6
	v_ashrrev_i32_e32 v14, 5, v10
	v_lshlrev_b32_e32 v10, 7, v14
	v_ashrrev_i32_e32 v11, 31, v10
	v_lshl_add_u64 v[10:11], v[10:11], 2, v[4:5]
	global_load_dwordx4 v[10:13], v[10:11], off
	v_cmp_le_i32_e64 s[4:5], v9, v14
	v_cmp_lt_i32_e32 vcc, v9, v14
	s_waitcnt vmcnt(0)
	v_cndmask_b32_e64 v10, 0, v10, s[4:5]
	v_bfe_u32 v15, v10, 16, 1
	v_cndmask_b32_e32 v11, 0, v11, vcc
	v_add3_u32 v10, v10, v15, s20
	v_bfe_u32 v15, v11, 16, 1
	v_lshrrev_b32_e32 v10, 16, v10
	v_add3_u32 v11, v11, v15, s20
	v_cmp_le_i32_e32 vcc, v8, v14
	v_and_or_b32 v10, v11, s33, v10
	s_nop 0
	v_cndmask_b32_e32 v11, 0, v12, vcc
	v_bfe_u32 v12, v11, 16, 1
	v_cmp_le_i32_e32 vcc, v7, v14
	v_add3_u32 v11, v11, v12, s20
	v_lshrrev_b32_e32 v11, 16, v11
	v_cndmask_b32_e32 v12, 0, v13, vcc
	v_bfe_u32 v13, v12, 16, 1
	v_add3_u32 v12, v12, v13, s20
	v_and_or_b32 v11, v12, s33, v11
	v_mad_u64_u32 v[12:13], s[4:5], v14, s6, v[2:3]
	ds_write_b64 v12, v[10:11]
	v_add_u32_e32 v10, 0x400, v6
	v_ashrrev_i32_e32 v14, 5, v10
	v_lshlrev_b32_e32 v10, 7, v14
	v_ashrrev_i32_e32 v11, 31, v10
	v_lshl_add_u64 v[10:11], v[10:11], 2, v[4:5]
	global_load_dwordx4 v[10:13], v[10:11], off
	v_cmp_le_i32_e64 s[4:5], v9, v14
	v_cmp_lt_i32_e32 vcc, v9, v14
	s_waitcnt vmcnt(0)
	v_cndmask_b32_e64 v10, 0, v10, s[4:5]
	v_bfe_u32 v15, v10, 16, 1
	v_cndmask_b32_e32 v11, 0, v11, vcc
	v_add3_u32 v10, v10, v15, s20
	v_bfe_u32 v15, v11, 16, 1
	v_lshrrev_b32_e32 v10, 16, v10
	v_add3_u32 v11, v11, v15, s20
	v_cmp_le_i32_e32 vcc, v8, v14
	v_and_or_b32 v10, v11, s33, v10
	s_nop 0
	v_cndmask_b32_e32 v11, 0, v12, vcc
	v_bfe_u32 v12, v11, 16, 1
	v_cmp_le_i32_e32 vcc, v7, v14
	v_add3_u32 v11, v11, v12, s20
	v_lshrrev_b32_e32 v11, 16, v11
	v_cndmask_b32_e32 v12, 0, v13, vcc
	v_bfe_u32 v13, v12, 16, 1
	v_add3_u32 v12, v12, v13, s20
	v_and_or_b32 v11, v12, s33, v11
	v_mad_u64_u32 v[12:13], s[4:5], v14, s6, v[2:3]
	ds_write_b64 v12, v[10:11]
	v_add_u32_e32 v10, 0x600, v6
	v_ashrrev_i32_e32 v14, 5, v10
	v_lshlrev_b32_e32 v10, 7, v14
	v_ashrrev_i32_e32 v11, 31, v10
	v_lshl_add_u64 v[10:11], v[10:11], 2, v[4:5]
	global_load_dwordx4 v[10:13], v[10:11], off
	v_cmp_le_i32_e64 s[4:5], v9, v14
	v_cmp_lt_i32_e32 vcc, v9, v14
	s_waitcnt vmcnt(0)
	v_cndmask_b32_e64 v10, 0, v10, s[4:5]
	v_bfe_u32 v15, v10, 16, 1
	v_cndmask_b32_e32 v11, 0, v11, vcc
	v_add3_u32 v10, v10, v15, s20
	v_bfe_u32 v15, v11, 16, 1
	v_lshrrev_b32_e32 v10, 16, v10
	v_add3_u32 v11, v11, v15, s20
	v_cmp_le_i32_e32 vcc, v8, v14
	v_and_or_b32 v10, v11, s33, v10
	s_nop 0
	v_cndmask_b32_e32 v11, 0, v12, vcc
	v_bfe_u32 v12, v11, 16, 1
	v_cmp_le_i32_e32 vcc, v7, v14
	v_add3_u32 v11, v11, v12, s20
	v_lshrrev_b32_e32 v11, 16, v11
	v_cndmask_b32_e32 v12, 0, v13, vcc
	v_bfe_u32 v13, v12, 16, 1
	v_add3_u32 v12, v12, v13, s20
	v_and_or_b32 v11, v12, s33, v11
	v_mad_u64_u32 v[12:13], s[4:5], v14, s6, v[2:3]
	ds_write_b64 v12, v[10:11]
	v_add_u32_e32 v10, 0x800, v6
	v_ashrrev_i32_e32 v14, 5, v10
	v_lshlrev_b32_e32 v10, 7, v14
	v_ashrrev_i32_e32 v11, 31, v10
	v_lshl_add_u64 v[10:11], v[10:11], 2, v[4:5]
	global_load_dwordx4 v[10:13], v[10:11], off
	v_cmp_le_i32_e64 s[4:5], v9, v14
	v_cmp_lt_i32_e32 vcc, v9, v14
	s_waitcnt vmcnt(0)
	v_cndmask_b32_e64 v10, 0, v10, s[4:5]
	v_bfe_u32 v15, v10, 16, 1
	v_cndmask_b32_e32 v11, 0, v11, vcc
	v_add3_u32 v10, v10, v15, s20
	v_bfe_u32 v15, v11, 16, 1
	v_lshrrev_b32_e32 v10, 16, v10
	v_add3_u32 v11, v11, v15, s20
	v_cmp_le_i32_e32 vcc, v8, v14
	v_and_or_b32 v10, v11, s33, v10
	s_nop 0
	v_cndmask_b32_e32 v11, 0, v12, vcc
	v_bfe_u32 v12, v11, 16, 1
	v_cmp_le_i32_e32 vcc, v7, v14
	v_add3_u32 v11, v11, v12, s20
	v_lshrrev_b32_e32 v11, 16, v11
	v_cndmask_b32_e32 v12, 0, v13, vcc
	v_bfe_u32 v13, v12, 16, 1
	v_add3_u32 v12, v12, v13, s20
	v_and_or_b32 v11, v12, s33, v11
	v_mad_u64_u32 v[12:13], s[4:5], v14, s6, v[2:3]
	ds_write_b64 v12, v[10:11]
	v_add_u32_e32 v10, 0xa00, v6
	v_ashrrev_i32_e32 v14, 5, v10
	v_lshlrev_b32_e32 v10, 7, v14
	v_ashrrev_i32_e32 v11, 31, v10
	v_lshl_add_u64 v[10:11], v[10:11], 2, v[4:5]
	global_load_dwordx4 v[10:13], v[10:11], off
	v_cmp_le_i32_e64 s[4:5], v9, v14
	v_cmp_lt_i32_e32 vcc, v9, v14
	s_waitcnt vmcnt(0)
	v_cndmask_b32_e64 v10, 0, v10, s[4:5]
	v_bfe_u32 v15, v10, 16, 1
	v_cndmask_b32_e32 v11, 0, v11, vcc
	v_add3_u32 v10, v10, v15, s20
	v_bfe_u32 v15, v11, 16, 1
	v_lshrrev_b32_e32 v10, 16, v10
	v_add3_u32 v11, v11, v15, s20
	v_cmp_le_i32_e32 vcc, v8, v14
	v_and_or_b32 v10, v11, s33, v10
	s_nop 0
	v_cndmask_b32_e32 v11, 0, v12, vcc
	v_bfe_u32 v12, v11, 16, 1
	v_cmp_le_i32_e32 vcc, v7, v14
	v_add3_u32 v11, v11, v12, s20
	v_lshrrev_b32_e32 v11, 16, v11
	v_cndmask_b32_e32 v12, 0, v13, vcc
	v_bfe_u32 v13, v12, 16, 1
	v_add3_u32 v12, v12, v13, s20
	v_and_or_b32 v11, v12, s33, v11
	v_mad_u64_u32 v[12:13], s[4:5], v14, s6, v[2:3]
	ds_write_b64 v12, v[10:11]
	v_add_u32_e32 v10, 0xc00, v6
	v_ashrrev_i32_e32 v14, 5, v10
	v_lshlrev_b32_e32 v10, 7, v14
	v_ashrrev_i32_e32 v11, 31, v10
	v_lshl_add_u64 v[10:11], v[10:11], 2, v[4:5]
	global_load_dwordx4 v[10:13], v[10:11], off
	v_cmp_le_i32_e64 s[4:5], v9, v14
	v_cmp_lt_i32_e32 vcc, v9, v14
	s_waitcnt vmcnt(0)
	v_cndmask_b32_e64 v10, 0, v10, s[4:5]
	v_bfe_u32 v15, v10, 16, 1
	v_cndmask_b32_e32 v11, 0, v11, vcc
	v_add3_u32 v10, v10, v15, s20
	v_bfe_u32 v15, v11, 16, 1
	v_lshrrev_b32_e32 v10, 16, v10
	v_add3_u32 v11, v11, v15, s20
	v_cmp_le_i32_e32 vcc, v8, v14
	v_and_or_b32 v10, v11, s33, v10
	s_nop 0
	v_cndmask_b32_e32 v11, 0, v12, vcc
	v_bfe_u32 v12, v11, 16, 1
	v_cmp_le_i32_e32 vcc, v7, v14
	v_add3_u32 v11, v11, v12, s20
	v_lshrrev_b32_e32 v11, 16, v11
	v_cndmask_b32_e32 v12, 0, v13, vcc
	v_bfe_u32 v13, v12, 16, 1
	v_add3_u32 v12, v12, v13, s20
	v_and_or_b32 v11, v12, s33, v11
	v_mad_u64_u32 v[12:13], s[4:5], v14, s6, v[2:3]
	ds_write_b64 v12, v[10:11]
	v_add_u32_e32 v10, 0xe00, v6
	v_ashrrev_i32_e32 v14, 5, v10
	v_lshlrev_b32_e32 v10, 7, v14
	v_ashrrev_i32_e32 v11, 31, v10
	v_lshl_add_u64 v[4:5], v[10:11], 2, v[4:5]
	global_load_dwordx4 v[10:13], v[4:5], off
	v_cmp_le_i32_e64 s[4:5], v9, v14
	v_cmp_lt_i32_e32 vcc, v9, v14
	s_waitcnt vmcnt(0)
	v_cndmask_b32_e64 v4, 0, v10, s[4:5]
	v_bfe_u32 v5, v4, 16, 1
	v_add3_u32 v4, v4, v5, s20
	v_cndmask_b32_e32 v5, 0, v11, vcc
	v_bfe_u32 v9, v5, 16, 1
	v_lshrrev_b32_e32 v4, 16, v4
	v_add3_u32 v5, v5, v9, s20
	v_cmp_le_i32_e32 vcc, v8, v14
	v_and_or_b32 v4, v5, s33, v4
	s_nop 0
	v_cndmask_b32_e32 v5, 0, v12, vcc
	v_cmp_le_i32_e32 vcc, v7, v14
	v_bfe_u32 v8, v5, 16, 1
	v_add3_u32 v5, v5, v8, s20
	v_cndmask_b32_e32 v7, 0, v13, vcc
	v_bfe_u32 v8, v7, 16, 1
	v_lshrrev_b32_e32 v5, 16, v5
	v_add3_u32 v7, v7, v8, s20
	v_mad_u64_u32 v[8:9], s[4:5], v14, s6, v[2:3]
	s_add_u32 s6, s0, 0x6b00000
	v_and_or_b32 v5, v7, s33, v5
	s_addc_u32 s7, s1, 0
	s_and_b32 s24, s9, 0xffffff80
	v_ashrrev_i32_e32 v12, 2, v6
	ds_write_b64 v8, v[4:5]
	v_add_u32_e32 v2, s24, v12
	v_mov_b64_e32 v[4:5], s[6:7]
	s_movk_i32 s4, 0x1200
	v_mad_i64_i32 v[4:5], s[4:5], v2, s4, v[4:5]
	v_lshlrev_b32_e32 v2, 4, v6
	s_lshl_b32 s34, s19, 7
	v_and_b32_e32 v22, 48, v2
	v_lshl_add_u64 v[4:5], v[4:5], 0, s[34:35]
	v_lshlrev_b32_e32 v2, 1, v22
	v_lshl_add_u64 v[8:9], v[4:5], 0, v[2:3]
	global_load_dwordx4 v[4:7], v[8:9], off offset:528
	s_nop 0
	global_load_dwordx4 v[8:11], v[8:9], off offset:512
	s_mov_b32 s4, 0xf800000
	s_lshl_b32 s25, s19, 6
	v_lshlrev_b32_e32 v18, 2, v22
	v_lshlrev_b32_e32 v37, 1, v12
	v_mul_u32_u24_e32 v22, 0x110, v22
	v_add3_u32 v22, 0, v37, v22
	s_waitcnt vmcnt(1)
	v_lshlrev_b32_e32 v28, 16, v4
	s_waitcnt vmcnt(0)
	v_and_b32_e32 v35, 0xffff0000, v8
	v_lshlrev_b32_e32 v13, 16, v8
	v_and_b32_e32 v27, 0xffff0000, v4
	v_mul_f32_e32 v4, v35, v35
	v_lshlrev_b32_e32 v34, 16, v9
	v_fmac_f32_e32 v4, v13, v13
	v_and_b32_e32 v33, 0xffff0000, v9
	v_fmac_f32_e32 v4, v34, v34
	v_lshlrev_b32_e32 v32, 16, v10
	v_fmac_f32_e32 v4, v33, v33
	v_and_b32_e32 v31, 0xffff0000, v10
	v_fmac_f32_e32 v4, v32, v32
	v_lshlrev_b32_e32 v30, 16, v11
	v_fmac_f32_e32 v4, v31, v31
	v_and_b32_e32 v29, 0xffff0000, v11
	v_fmac_f32_e32 v4, v30, v30
	v_fmac_f32_e32 v4, v29, v29
	v_fmac_f32_e32 v4, v28, v28
	v_lshlrev_b32_e32 v26, 16, v5
	v_fmac_f32_e32 v4, v27, v27
	v_and_b32_e32 v25, 0xffff0000, v5
	v_fmac_f32_e32 v4, v26, v26
	v_lshlrev_b32_e32 v24, 16, v6
	v_lshlrev_b32_e32 v5, 16, v7
	v_and_b32_e32 v2, 0xffff0000, v7
	v_fmac_f32_e32 v4, v25, v25
	v_and_b32_e32 v7, 64, v218
	v_and_b32_e32 v23, 0xffff0000, v6
	v_fmac_f32_e32 v4, v24, v24
	v_xor_b32_e32 v6, 1, v218
	v_add_u32_e32 v7, 64, v7
	v_fmac_f32_e32 v4, v23, v23
	v_cmp_lt_i32_e32 vcc, v6, v7
	v_fmac_f32_e32 v4, v5, v5
	v_fmac_f32_e32 v4, v2, v2
	v_cndmask_b32_e32 v6, v218, v6, vcc
	v_lshlrev_b32_e32 v6, 2, v6
	ds_bpermute_b32 v6, v6, v4
	s_waitcnt lgkmcnt(0)
	v_add_f32_e32 v4, v4, v6
	v_xor_b32_e32 v6, 2, v218
	v_cmp_lt_i32_e32 vcc, v6, v7
	s_nop 1
	v_cndmask_b32_e32 v6, v218, v6, vcc
	v_lshlrev_b32_e32 v6, 2, v6
	ds_bpermute_b32 v6, v6, v4
	s_waitcnt lgkmcnt(0)
	v_add_f32_e32 v4, v4, v6
	v_fmamk_f32 v4, v4, 0x3c800000, v215
	v_cmp_gt_f32_e32 vcc, s4, v4
	v_mul_f32_e32 v6, 0x4f800000, v4
	s_nop 0
	v_cndmask_b32_e32 v6, v4, v6, vcc
	v_sqrt_f32_e32 v7, v6
	v_mov_b32_e32 v4, 0
	v_add_u32_e32 v8, -1, v7
	v_fma_f32 v9, -v8, v7, v6
	v_cmp_ge_f32_e64 s[4:5], 0, v9
	v_add_u32_e32 v9, 1, v7
	s_nop 0
	v_cndmask_b32_e64 v8, v7, v8, s[4:5]
	v_fma_f32 v7, -v9, v7, v6
	v_cmp_lt_f32_e64 s[4:5], 0, v7
	s_nop 1
	v_cndmask_b32_e64 v7, v8, v9, s[4:5]
	v_mul_f32_e32 v8, 0x37800000, v7
	v_cndmask_b32_e32 v7, v7, v8, vcc
	v_cmp_class_f32_e32 vcc, v6, v216
	s_nop 1
	v_cndmask_b32_e32 v6, v7, v6, vcc
	v_div_scale_f32 v7, s[4:5], v6, v6, 1.0
	v_rcp_f32_e32 v8, v7
	s_lshl_b64 s[4:5], s[22:23], 2
	s_add_u32 s4, s44, s4
	s_addc_u32 s5, s45, s5
	v_fma_f32 v9, -v7, v8, 1.0
	v_fmac_f32_e32 v8, v9, v8
	v_div_scale_f32 v9, vcc, 1.0, v6, 1.0
	v_mul_f32_e32 v10, v9, v8
	v_fma_f32 v11, -v7, v10, v9
	v_fmac_f32_e32 v10, v11, v8
	v_fma_f32 v7, -v7, v10, v9
	s_lshl_b32 s19, s19, 8
	v_div_fmas_f32 v7, v7, v8, v10
	s_add_u32 s4, s4, s19
	v_div_fixup_f32 v36, v7, v6, 1.0
	s_addc_u32 s5, s5, 0
	v_mul_f32_e32 v38, v36, v13
	global_load_dwordx4 v[6:9], v18, s[4:5] offset:48
	global_load_dwordx4 v[10:13], v18, s[4:5] offset:32
	global_load_dwordx4 v[14:17], v18, s[4:5] offset:16
	s_nop 0
	global_load_dwordx4 v[18:21], v18, s[4:5]
	v_mul_f32_e32 v5, v36, v5
	v_mul_f32_e32 v2, v36, v2
	v_readlane_b32 s4, v254, 56
	s_waitcnt vmcnt(3)
	v_mul_f32_e32 v5, v5, v8
	v_mul_f32_e32 v2, v2, v9
	v_mov_b32_e32 v8, v4
	s_waitcnt vmcnt(0)
	v_mul_f32_e32 v18, v18, v38
	v_bfe_u32 v38, v18, 16, 1
	v_add3_u32 v18, v18, v38, s20
	ds_write_b16_d16_hi v22, v18 offset:34816
	v_mul_f32_e32 v18, v36, v35
	v_mul_f32_e32 v18, v19, v18
	v_bfe_u32 v19, v18, 16, 1
	v_add3_u32 v18, v18, v19, s20
	ds_write_b16_d16_hi v22, v18 offset:35088
	v_mul_f32_e32 v18, v36, v34
	v_mul_f32_e32 v18, v20, v18
	v_bfe_u32 v19, v18, 16, 1
	v_add3_u32 v18, v18, v19, s20
	ds_write_b16_d16_hi v22, v18 offset:35360
	v_mul_f32_e32 v18, v36, v33
	v_mul_f32_e32 v18, v21, v18
	v_bfe_u32 v19, v18, 16, 1
	v_add3_u32 v18, v18, v19, s20
	ds_write_b16_d16_hi v22, v18 offset:35632
	v_mul_f32_e32 v18, v36, v32
	v_mul_f32_e32 v14, v14, v18
	v_bfe_u32 v18, v14, 16, 1
	v_add3_u32 v14, v14, v18, s20
	ds_write_b16_d16_hi v22, v14 offset:35904
	v_mul_f32_e32 v14, v36, v31
	v_mul_f32_e32 v14, v15, v14
	v_bfe_u32 v15, v14, 16, 1
	v_add3_u32 v14, v14, v15, s20
	ds_write_b16_d16_hi v22, v14 offset:36176
	v_mul_f32_e32 v14, v36, v30
	v_mul_f32_e32 v14, v16, v14
	v_bfe_u32 v15, v14, 16, 1
	v_add3_u32 v14, v14, v15, s20
	ds_write_b16_d16_hi v22, v14 offset:36448
	v_mul_f32_e32 v14, v36, v29
	v_mul_f32_e32 v14, v17, v14
	v_bfe_u32 v15, v14, 16, 1
	v_add3_u32 v14, v14, v15, s20
	ds_write_b16_d16_hi v22, v14 offset:36720
	v_mul_f32_e32 v14, v36, v28
	v_mul_f32_e32 v10, v10, v14
	v_bfe_u32 v14, v10, 16, 1
	v_add3_u32 v10, v10, v14, s20
	ds_write_b16_d16_hi v22, v10 offset:36992
	v_mul_f32_e32 v10, v36, v27
	v_mul_f32_e32 v10, v11, v10
	v_bfe_u32 v11, v10, 16, 1
	v_add3_u32 v10, v10, v11, s20
	ds_write_b16_d16_hi v22, v10 offset:37264
	v_mul_f32_e32 v10, v36, v26
	v_mul_f32_e32 v10, v10, v12
	v_bfe_u32 v11, v10, 16, 1
	v_add3_u32 v10, v10, v11, s20
	ds_write_b16_d16_hi v22, v10 offset:37536
	v_mul_f32_e32 v10, v36, v25
	v_mul_f32_e32 v10, v10, v13
	v_bfe_u32 v11, v10, 16, 1
	v_add3_u32 v10, v10, v11, s20
	ds_write_b16_d16_hi v22, v10 offset:37808
	v_mul_f32_e32 v10, v36, v24
	v_mul_f32_e32 v6, v10, v6
	v_bfe_u32 v10, v6, 16, 1
	v_add3_u32 v6, v6, v10, s20
	ds_write_b16_d16_hi v22, v6 offset:38080
	v_mul_f32_e32 v6, v36, v23
	v_mul_f32_e32 v6, v6, v7
	v_bfe_u32 v7, v6, 16, 1
	v_add3_u32 v6, v6, v7, s20
	ds_write_b16_d16_hi v22, v6 offset:38352
	v_bfe_u32 v6, v5, 16, 1
	v_add3_u32 v5, v5, v6, s20
	ds_write_b16_d16_hi v22, v5 offset:38624
	v_bfe_u32 v5, v2, 16, 1
	v_add3_u32 v2, v2, v5, s20
	ds_write_b16_d16_hi v22, v2 offset:38896
	v_and_b32_e32 v2, 31, v1
	v_ashrrev_i32_e32 v1, 5, v1
	v_mul_u32_u24_e32 v5, 0x88, v2
	v_lshlrev_b32_e32 v5, 1, v5
	v_lshlrev_b32_e32 v6, 4, v1
	v_add3_u32 v20, s4, v5, v6
	v_readlane_b32 s4, v254, 53
	v_mov_b32_e32 v7, v4
	v_mov_b32_e32 v9, v4
	v_add3_u32 v21, v6, v5, s4
	v_mov_b32_e32 v5, v4
	v_mov_b32_e32 v6, v4
	v_mov_b32_e32 v10, v4
	v_mov_b32_e32 v11, v4
	v_mov_b32_e32 v12, v4
	v_mov_b32_e32 v13, v4
	v_mov_b32_e32 v14, v4
	v_mov_b32_e32 v15, v4
	v_mov_b32_e32 v16, v4
	v_mov_b32_e32 v17, v4
	v_mov_b32_e32 v18, v4
	v_mov_b32_e32 v19, v4
	s_waitcnt lgkmcnt(0)
	s_barrier

.LBB0_363:
	s_lshl_b32 s10, s26, 14
	v_readlane_b32 s11, v252, 6
	v_readlane_b32 s74, v252, 5
	v_readlane_b32 s75, v255, 62
	s_nop 3
	s_and_b32 s74, s74, 7
	s_lshl_b32 s74, s74, 5
	s_cmp_lg_u32 s75, 0
	s_cselect_b32 s74, s74, 0
	s_add_i32 s11, s11, s74
	s_branch .LBB0_365

.LBB0_365:
	v_readlane_b32 s0, v252, 4
	v_readlane_b32 s75, v255, 62
	s_nop 3
	s_cmp_lg_u32 s75, 0
	s_cselect_b32 s75, 32, s0
	s_add_i32 s14, s11, s75
	s_cmpk_gt_i32 s14, 0x1ff
	s_mov_b64 s[0:1], -1
	s_cbranch_scc0 .LBB0_379
	v_mov_b32_e32 v1, v214
	v_mov_b32_e32 v12, v0
	s_load_dwordx2 s[0:1], s[94:95], 0xd8
	s_lshl_b32 s4, s11, 5
	s_and_b32 s23, s4, 0x780
	v_ashrrev_i32_e32 v13, 2, v12
	s_and_b32 s15, s4, 0xfffff800
	v_add_u32_e32 v80, s23, v13
	v_add_u32_e32 v2, s15, v80
	s_waitcnt lgkmcnt(0)
	v_mov_b64_e32 v[4:5], s[0:1]
	s_movk_i32 s4, 0x1200
	s_and_b32 s24, s11, 3
	v_mad_i64_i32 v[4:5], s[4:5], v2, s4, v[4:5]
	v_lshlrev_b32_e32 v2, 4, v12
	s_lshl_b32 s34, s24, 7
	v_and_b32_e32 v2, 48, v2
	v_lshl_add_u64 v[4:5], v[4:5], 0, s[34:35]
	v_lshlrev_b32_e32 v2, 1, v2
	v_lshl_add_u64 v[8:9], v[4:5], 0, v[2:3]
	s_mov_b32 s4, 0x6b00000
	v_add_co_u32_e32 v4, vcc, s4, v8
	s_mov_b64 s[4:5], 0x6b00c00
	s_nop 0
	v_addc_co_u32_e32 v5, vcc, 0, v9, vcc
	v_cmp_gt_i32_e32 vcc, 1, v80
	global_load_dwordx4 v[4:7], v[4:5], off offset:3072
	v_lshl_add_u64 v[42:43], v[8:9], 0, s[4:5]
	v_cndmask_b32_e64 v15, -1, 0, vcc
	v_cndmask_b32_e64 v14, v221, 0, vcc
	global_load_dwordx4 v[8:11], v[42:43], off offset:16
	v_lshl_add_u64 v[14:15], v[42:43], 0, v[14:15]
	global_load_dwordx4 v[30:33], v[14:15], off
	global_load_dwordx4 v[34:37], v[14:15], off offset:16
	v_cmp_gt_i32_e64 s[4:5], 0, v80
	s_cmp_lt_i32 s24, 2
	s_waitcnt vmcnt(3)
	v_lshlrev_b32_e32 v23, 16, v5
	v_lshlrev_b32_e32 v22, 16, v4
	v_and_b32_e32 v25, 0xffff0000, v5
	v_and_b32_e32 v24, 0xffff0000, v4
	v_lshlrev_b32_e32 v27, 16, v7
	v_lshlrev_b32_e32 v26, 16, v6
	v_and_b32_e32 v29, 0xffff0000, v7
	v_and_b32_e32 v28, 0xffff0000, v6
	s_waitcnt vmcnt(2)
	v_lshlrev_b32_e32 v14, 16, v8
	v_and_b32_e32 v16, 0xffff0000, v8
	v_add_f32_e32 v4, 0, v22
	v_add_f32_e32 v5, 0, v24
	v_add_f32_e32 v7, 0, v23
	v_add_f32_e32 v8, 0, v25
	s_waitcnt vmcnt(1)
	v_lshlrev_b32_e32 v51, 16, v30
	v_and_b32_e32 v52, 0xffff0000, v30
	v_lshlrev_b32_e32 v53, 16, v31
	v_and_b32_e32 v54, 0xffff0000, v31
	v_lshlrev_b32_e32 v15, 16, v9
	v_and_b32_e32 v17, 0xffff0000, v9
	v_lshlrev_b32_e32 v19, 16, v11
	v_lshlrev_b32_e32 v18, 16, v10
	v_and_b32_e32 v21, 0xffff0000, v11
	v_and_b32_e32 v20, 0xffff0000, v10
	v_add_f32_e32 v9, 0, v26
	v_add_f32_e32 v10, 0, v28
	v_add_f32_e32 v11, 0, v27
	v_add_f32_e32 v38, 0, v29
	v_lshlrev_b32_e32 v55, 16, v32
	v_and_b32_e32 v56, 0xffff0000, v32
	v_lshlrev_b32_e32 v57, 16, v33
	v_and_b32_e32 v58, 0xffff0000, v33
	s_waitcnt vmcnt(0)
	v_lshlrev_b32_e32 v59, 16, v34
	v_and_b32_e32 v60, 0xffff0000, v34
	v_lshlrev_b32_e32 v61, 16, v35
	v_and_b32_e32 v62, 0xffff0000, v35
	v_cndmask_b32_e64 v4, v4, 0, s[4:5]
	v_cndmask_b32_e64 v6, v5, 0, s[4:5]
	v_cndmask_b32_e64 v5, v7, 0, s[4:5]
	v_cndmask_b32_e64 v7, v8, 0, s[4:5]
	v_cndmask_b32_e64 v30, v51, 0, vcc
	v_cndmask_b32_e64 v34, v52, 0, vcc
	v_cndmask_b32_e64 v31, v53, 0, vcc
	v_cndmask_b32_e64 v35, v54, 0, vcc
	v_add_f32_e32 v39, 0, v14
	v_add_f32_e32 v40, 0, v16
	v_add_f32_e32 v41, 0, v15
	v_add_f32_e32 v45, 0, v17
	v_add_f32_e32 v47, 0, v20
	v_add_f32_e32 v49, 0, v19
	v_add_f32_e32 v50, 0, v21
	v_cndmask_b32_e64 v8, v9, 0, s[4:5]
	v_cndmask_b32_e64 v10, v10, 0, s[4:5]
	v_cndmask_b32_e64 v9, v11, 0, s[4:5]
	v_cndmask_b32_e64 v11, v38, 0, s[4:5]
	v_pk_add_f32 v[32:33], v[4:5], v[30:31]
	v_pk_add_f32 v[30:31], v[6:7], v[34:35]
	v_cndmask_b32_e64 v4, v55, 0, vcc
	v_cndmask_b32_e64 v6, v56, 0, vcc
	v_cndmask_b32_e64 v5, v57, 0, vcc
	v_cndmask_b32_e64 v7, v58, 0, vcc
	v_add_f32_e32 v46, 0, v18
	v_lshlrev_b32_e32 v63, 16, v36
	v_and_b32_e32 v64, 0xffff0000, v36
	v_cndmask_b32_e64 v38, v39, 0, s[4:5]
	v_cndmask_b32_e64 v44, v40, 0, s[4:5]
	v_cndmask_b32_e64 v39, v41, 0, s[4:5]
	v_cndmask_b32_e64 v45, v45, 0, s[4:5]
	v_cndmask_b32_e64 v48, v47, 0, s[4:5]
	v_cndmask_b32_e64 v47, v49, 0, s[4:5]
	v_cndmask_b32_e64 v49, v50, 0, s[4:5]
	v_lshlrev_b32_e32 v50, 16, v37
	v_and_b32_e32 v65, 0xffff0000, v37
	v_pk_add_f32 v[36:37], v[8:9], v[4:5]
	v_pk_add_f32 v[34:35], v[10:11], v[6:7]
	v_cndmask_b32_e64 v4, v59, 0, vcc
	v_cndmask_b32_e64 v6, v60, 0, vcc
	v_cndmask_b32_e64 v5, v61, 0, vcc
	v_cndmask_b32_e64 v7, v62, 0, vcc
	v_cndmask_b32_e64 v46, v46, 0, s[4:5]
	v_pk_add_f32 v[40:41], v[38:39], v[4:5]
	v_pk_add_f32 v[38:39], v[44:45], v[6:7]
	v_cndmask_b32_e64 v4, v63, 0, vcc
	v_cndmask_b32_e64 v6, v64, 0, vcc
	v_cndmask_b32_e64 v5, v50, 0, vcc
	v_cndmask_b32_e64 v7, v65, 0, vcc
	v_pk_add_f32 v[46:47], v[46:47], v[4:5]
	v_pk_add_f32 v[44:45], v[48:49], v[6:7]
	s_mov_b64 s[4:5], -1
	s_cbranch_scc1 .LBB0_372
	s_mov_b64 s[18:19], -1
	s_cmp_gt_i32 s24, 2
	v_cmp_gt_i32_e64 s[8:9], 4, v80
	v_cmp_gt_i32_e64 s[6:7], 5, v80
	v_cmp_gt_i32_e64 s[4:5], 6, v80
	v_cmp_gt_i32_e32 vcc, 7, v80
	s_cbranch_scc0 .LBB0_369
	v_cmp_gt_i32_e64 s[42:43], 2, v80
	s_mov_b64 s[18:19], 0
	s_nop 0
	v_cndmask_b32_e64 v5, -1, 0, s[42:43]
	v_cndmask_b32_e64 v4, v220, 0, s[42:43]
	v_lshl_add_u64 v[8:9], v[42:43], 0, v[4:5]
	global_load_dwordx4 v[4:7], v[8:9], off offset:16
	s_nop 0
	global_load_dwordx4 v[8:11], v[8:9], off
	s_waitcnt vmcnt(1)
	v_lshlrev_b32_e32 v52, 16, v4
	s_waitcnt vmcnt(0)
	v_lshlrev_b32_e32 v48, 16, v8
	v_and_b32_e32 v8, 0xffff0000, v8
	v_lshlrev_b32_e32 v49, 16, v9
	v_and_b32_e32 v4, 0xffff0000, v4
	v_cndmask_b32_e64 v8, v8, 0, s[42:43]
	v_and_b32_e32 v9, 0xffff0000, v9
	v_lshlrev_b32_e32 v53, 16, v5
	v_add_f32_e32 v56, v30, v8
	v_cndmask_b32_e64 v8, v49, 0, s[42:43]
	v_cndmask_b32_e64 v4, v4, 0, s[42:43]
	v_lshlrev_b32_e32 v50, 16, v10
	v_and_b32_e32 v5, 0xffff0000, v5
	v_add_f32_e32 v49, v33, v8
	v_cndmask_b32_e64 v8, v9, 0, s[42:43]
	v_add_f32_e32 v60, v38, v4
	v_cndmask_b32_e64 v4, v53, 0, s[42:43]
	v_and_b32_e32 v10, 0xffff0000, v10
	v_lshlrev_b32_e32 v54, 16, v6
	v_add_f32_e32 v57, v31, v8
	v_cndmask_b32_e64 v8, v50, 0, s[42:43]
	v_add_f32_e32 v53, v41, v4
	v_cndmask_b32_e64 v4, v5, 0, s[42:43]
	v_lshlrev_b32_e32 v51, 16, v11
	v_and_b32_e32 v6, 0xffff0000, v6
	v_add_f32_e32 v50, v36, v8
	v_cndmask_b32_e64 v8, v10, 0, s[42:43]
	v_add_f32_e32 v61, v39, v4
	v_cndmask_b32_e64 v4, v54, 0, s[42:43]
	v_and_b32_e32 v11, 0xffff0000, v11
	v_lshlrev_b32_e32 v55, 16, v7
	v_add_f32_e32 v58, v34, v8
	v_cndmask_b32_e64 v8, v51, 0, s[42:43]
	v_add_f32_e32 v54, v46, v4
	v_cndmask_b32_e64 v4, v6, 0, s[42:43]
	v_and_b32_e32 v7, 0xffff0000, v7
	v_add_f32_e32 v51, v37, v8
	v_cndmask_b32_e64 v8, v11, 0, s[42:43]
	v_add_f32_e32 v62, v44, v4
	v_cndmask_b32_e64 v4, v55, 0, s[42:43]
	v_cndmask_b32_e64 v48, v48, 0, s[42:43]
	v_add_f32_e32 v59, v35, v8
	v_cndmask_b32_e64 v8, v52, 0, s[42:43]
	v_add_f32_e32 v55, v47, v4
	v_cndmask_b32_e64 v4, v7, 0, s[42:43]
	v_cmp_gt_i32_e64 s[42:43], 3, v80
	v_add_f32_e32 v63, v45, v4
	v_add_f32_e32 v52, v40, v8
	v_cndmask_b32_e64 v5, -1, 0, s[42:43]
	v_cndmask_b32_e64 v4, v219, 0, s[42:43]
	v_lshl_add_u64 v[8:9], v[42:43], 0, v[4:5]
	global_load_dwordx4 v[4:7], v[8:9], off offset:16
	s_nop 0
	global_load_dwordx4 v[8:11], v[8:9], off
	v_add_f32_e32 v48, v32, v48
	s_waitcnt vmcnt(1)
	v_lshlrev_b32_e32 v68, 16, v4
	s_waitcnt vmcnt(0)
	v_lshlrev_b32_e32 v64, 16, v8
	v_and_b32_e32 v8, 0xffff0000, v8
	v_and_b32_e32 v4, 0xffff0000, v4
	v_lshlrev_b32_e32 v65, 16, v9
	v_lshlrev_b32_e32 v69, 16, v5
	v_cndmask_b32_e64 v8, v8, 0, s[42:43]
	v_cndmask_b32_e64 v4, v4, 0, s[42:43]
	v_and_b32_e32 v9, 0xffff0000, v9
	v_and_b32_e32 v5, 0xffff0000, v5
	v_add_f32_e32 v56, v56, v8
	v_cndmask_b32_e64 v8, v65, 0, s[42:43]
	v_add_f32_e32 v60, v60, v4
	v_cndmask_b32_e64 v4, v69, 0, s[42:43]
	v_lshlrev_b32_e32 v66, 16, v10
	v_lshlrev_b32_e32 v70, 16, v6
	v_add_f32_e32 v49, v49, v8
	v_cndmask_b32_e64 v8, v9, 0, s[42:43]
	v_add_f32_e32 v53, v53, v4
	v_cndmask_b32_e64 v4, v5, 0, s[42:43]
	v_and_b32_e32 v10, 0xffff0000, v10
	v_and_b32_e32 v6, 0xffff0000, v6
	v_add_f32_e32 v57, v57, v8
	v_cndmask_b32_e64 v8, v66, 0, s[42:43]
	v_add_f32_e32 v61, v61, v4
	v_cndmask_b32_e64 v4, v70, 0, s[42:43]
	v_lshlrev_b32_e32 v67, 16, v11
	v_lshlrev_b32_e32 v71, 16, v7
	v_add_f32_e32 v50, v50, v8
	v_cndmask_b32_e64 v8, v10, 0, s[42:43]
	v_add_f32_e32 v54, v54, v4
	v_cndmask_b32_e64 v4, v6, 0, s[42:43]
	v_and_b32_e32 v11, 0xffff0000, v11
	v_and_b32_e32 v7, 0xffff0000, v7
	v_add_f32_e32 v58, v58, v8
	v_cndmask_b32_e64 v8, v67, 0, s[42:43]
	v_add_f32_e32 v62, v62, v4
	v_cndmask_b32_e64 v4, v71, 0, s[42:43]
	v_add_f32_e32 v51, v51, v8
	v_cndmask_b32_e64 v8, v11, 0, s[42:43]
	v_add_f32_e32 v55, v55, v4
	v_cndmask_b32_e64 v4, v7, 0, s[42:43]
	v_add_f32_e32 v59, v59, v8
	v_cndmask_b32_e64 v8, v68, 0, s[42:43]
	v_add_f32_e32 v63, v63, v4
	v_cndmask_b32_e64 v5, -1, 0, s[8:9]
	v_cndmask_b32_e64 v4, v226, 0, s[8:9]
	v_add_f32_e32 v52, v52, v8
	v_lshl_add_u64 v[8:9], v[42:43], 0, v[4:5]
	global_load_dwordx4 v[4:7], v[8:9], off offset:16
	s_nop 0
	global_load_dwordx4 v[8:11], v[8:9], off
	v_cndmask_b32_e64 v64, v64, 0, s[42:43]
	v_add_f32_e32 v48, v48, v64
	s_waitcnt vmcnt(1)
	v_lshlrev_b32_e32 v68, 16, v4
	s_waitcnt vmcnt(0)
	v_lshlrev_b32_e32 v64, 16, v8
	v_and_b32_e32 v69, 0xffff0000, v4
	v_cndmask_b32_e64 v4, v64, 0, s[8:9]
	v_and_b32_e32 v8, 0xffff0000, v8
	v_lshlrev_b32_e32 v65, 16, v9
	v_and_b32_e32 v9, 0xffff0000, v9
	v_lshlrev_b32_e32 v66, 16, v10
	v_and_b32_e32 v10, 0xffff0000, v10
	v_lshlrev_b32_e32 v67, 16, v11
	v_lshlrev_b32_e32 v72, 16, v6
	v_add_f32_e32 v4, v48, v4
	v_cndmask_b32_e64 v48, v68, 0, s[8:9]
	v_lshlrev_b32_e32 v70, 16, v5
	v_and_b32_e32 v71, 0xffff0000, v5
	v_and_b32_e32 v73, 0xffff0000, v6
	v_lshlrev_b32_e32 v74, 16, v7
	v_and_b32_e32 v75, 0xffff0000, v7
	v_cndmask_b32_e64 v5, v8, 0, s[8:9]
	v_cndmask_b32_e64 v6, v65, 0, s[8:9]
	v_cndmask_b32_e64 v7, v9, 0, s[8:9]
	v_cndmask_b32_e64 v8, v66, 0, s[8:9]
	v_cndmask_b32_e64 v9, v10, 0, s[8:9]
	v_cndmask_b32_e64 v10, v67, 0, s[8:9]
	v_add_f32_e32 v48, v52, v48
	v_cndmask_b32_e64 v52, v72, 0, s[8:9]
	v_and_b32_e32 v11, 0xffff0000, v11
	v_add_f32_e32 v5, v56, v5
	v_add_f32_e32 v6, v49, v6
	v_add_f32_e32 v7, v57, v7
	v_add_f32_e32 v8, v50, v8
	v_add_f32_e32 v10, v51, v10
	v_cndmask_b32_e64 v49, v69, 0, s[8:9]
	v_cndmask_b32_e64 v50, v70, 0, s[8:9]
	v_cndmask_b32_e64 v51, v71, 0, s[8:9]
	v_add_f32_e32 v52, v54, v52
	v_cndmask_b32_e64 v54, v74, 0, s[8:9]
	v_cndmask_b32_e64 v57, -1, 0, s[6:7]
	v_cndmask_b32_e64 v56, v227, 0, s[6:7]
	v_cndmask_b32_e64 v11, v11, 0, s[8:9]
	v_add_f32_e32 v49, v60, v49
	v_add_f32_e32 v50, v53, v50
	v_add_f32_e32 v51, v61, v51
	v_cndmask_b32_e64 v53, v73, 0, s[8:9]
	v_add_f32_e32 v54, v55, v54
	v_cndmask_b32_e64 v55, v75, 0, s[8:9]
	v_lshl_add_u64 v[60:61], v[42:43], 0, v[56:57]
	v_add_f32_e32 v9, v58, v9
	v_add_f32_e32 v11, v59, v11
	v_add_f32_e32 v53, v62, v53
	v_add_f32_e32 v55, v63, v55
	global_load_dwordx4 v[56:59], v[60:61], off offset:16
	s_nop 0
	global_load_dwordx4 v[60:63], v[60:61], off
	s_waitcnt vmcnt(1)
	v_lshlrev_b32_e32 v68, 16, v56
	s_waitcnt vmcnt(0)
	v_lshlrev_b32_e32 v64, 16, v60
	v_and_b32_e32 v60, 0xffff0000, v60
	v_cndmask_b32_e64 v64, v64, 0, s[6:7]
	v_lshlrev_b32_e32 v65, 16, v61
	v_add_f32_e32 v64, v4, v64
	v_cndmask_b32_e64 v4, v60, 0, s[6:7]
	v_and_b32_e32 v61, 0xffff0000, v61
	v_add_f32_e32 v60, v5, v4
	v_cndmask_b32_e64 v4, v65, 0, s[6:7]
	v_lshlrev_b32_e32 v66, 16, v62
	v_add_f32_e32 v65, v6, v4
	v_cndmask_b32_e64 v4, v61, 0, s[6:7]
	v_and_b32_e32 v62, 0xffff0000, v62
	v_add_f32_e32 v61, v7, v4
	v_cndmask_b32_e64 v4, v66, 0, s[6:7]
	v_lshlrev_b32_e32 v67, 16, v63
	v_add_f32_e32 v66, v8, v4
	v_cndmask_b32_e64 v4, v62, 0, s[6:7]
	v_and_b32_e32 v63, 0xffff0000, v63
	v_add_f32_e32 v62, v9, v4
	v_cndmask_b32_e64 v4, v67, 0, s[6:7]
	v_add_f32_e32 v67, v10, v4
	v_cndmask_b32_e64 v4, v63, 0, s[6:7]
	v_and_b32_e32 v56, 0xffff0000, v56
	v_add_f32_e32 v63, v11, v4
	v_cndmask_b32_e64 v4, v68, 0, s[6:7]
	v_lshlrev_b32_e32 v69, 16, v57
	v_add_f32_e32 v48, v48, v4
	v_cndmask_b32_e64 v4, v56, 0, s[6:7]
	v_and_b32_e32 v57, 0xffff0000, v57
	v_add_f32_e32 v49, v49, v4
	v_cndmask_b32_e64 v4, v69, 0, s[6:7]
	v_lshlrev_b32_e32 v70, 16, v58
	v_add_f32_e32 v50, v50, v4
	v_cndmask_b32_e64 v4, v57, 0, s[6:7]
	v_and_b32_e32 v58, 0xffff0000, v58
	v_add_f32_e32 v51, v51, v4
	v_cndmask_b32_e64 v4, v70, 0, s[6:7]
	v_lshlrev_b32_e32 v71, 16, v59
	v_add_f32_e32 v52, v52, v4
	v_cndmask_b32_e64 v4, v58, 0, s[6:7]
	v_and_b32_e32 v59, 0xffff0000, v59
	v_add_f32_e32 v53, v53, v4
	v_cndmask_b32_e64 v4, v71, 0, s[6:7]
	v_add_f32_e32 v54, v54, v4
	v_cndmask_b32_e64 v4, v59, 0, s[6:7]
	v_add_f32_e32 v55, v55, v4
	v_cndmask_b32_e64 v5, -1, 0, s[4:5]
	v_cndmask_b32_e64 v4, v228, 0, s[4:5]
	v_lshl_add_u64 v[8:9], v[42:43], 0, v[4:5]
	global_load_dwordx4 v[4:7], v[8:9], off offset:16
	s_nop 0
	global_load_dwordx4 v[8:11], v[8:9], off
	s_waitcnt vmcnt(1)
	v_lshlrev_b32_e32 v68, 16, v4
	s_waitcnt vmcnt(0)
	v_lshlrev_b32_e32 v56, 16, v8
	v_and_b32_e32 v8, 0xffff0000, v8
	v_and_b32_e32 v4, 0xffff0000, v4
	v_lshlrev_b32_e32 v57, 16, v9
	v_lshlrev_b32_e32 v69, 16, v5
	v_cndmask_b32_e64 v8, v8, 0, s[4:5]
	v_cndmask_b32_e64 v4, v4, 0, s[4:5]
	v_and_b32_e32 v9, 0xffff0000, v9
	v_and_b32_e32 v5, 0xffff0000, v5
	v_add_f32_e32 v60, v60, v8
	v_cndmask_b32_e64 v8, v57, 0, s[4:5]
	v_add_f32_e32 v49, v49, v4
	v_cndmask_b32_e64 v4, v69, 0, s[4:5]
	v_lshlrev_b32_e32 v58, 16, v10
	v_lshlrev_b32_e32 v70, 16, v6
	v_add_f32_e32 v57, v65, v8
	v_cndmask_b32_e64 v8, v9, 0, s[4:5]
	v_add_f32_e32 v50, v50, v4
	v_cndmask_b32_e64 v4, v5, 0, s[4:5]
	v_and_b32_e32 v10, 0xffff0000, v10
	v_and_b32_e32 v6, 0xffff0000, v6
	v_add_f32_e32 v61, v61, v8
	v_cndmask_b32_e64 v8, v58, 0, s[4:5]
	v_add_f32_e32 v51, v51, v4
	v_cndmask_b32_e64 v4, v70, 0, s[4:5]
	v_lshlrev_b32_e32 v59, 16, v11
	v_lshlrev_b32_e32 v71, 16, v7
	v_add_f32_e32 v58, v66, v8
	v_cndmask_b32_e64 v8, v10, 0, s[4:5]
	v_add_f32_e32 v52, v52, v4
	v_cndmask_b32_e64 v4, v6, 0, s[4:5]
	v_and_b32_e32 v11, 0xffff0000, v11
	v_and_b32_e32 v7, 0xffff0000, v7
	v_add_f32_e32 v62, v62, v8
	v_cndmask_b32_e64 v8, v59, 0, s[4:5]
	v_add_f32_e32 v53, v53, v4
	v_cndmask_b32_e64 v4, v71, 0, s[4:5]
	v_add_f32_e32 v59, v67, v8
	v_cndmask_b32_e64 v8, v11, 0, s[4:5]
	v_add_f32_e32 v54, v54, v4
	v_cndmask_b32_e64 v4, v7, 0, s[4:5]
	v_add_f32_e32 v63, v63, v8
	v_cndmask_b32_e64 v8, v68, 0, s[4:5]
	v_add_f32_e32 v55, v55, v4
	v_cndmask_b32_e64 v5, -1, 0, vcc
	v_cndmask_b32_e64 v4, v229, 0, vcc
	v_add_f32_e32 v48, v48, v8
	v_lshl_add_u64 v[8:9], v[42:43], 0, v[4:5]
	global_load_dwordx4 v[4:7], v[8:9], off offset:16
	s_nop 0
	global_load_dwordx4 v[8:11], v[8:9], off
	v_cndmask_b32_e64 v56, v56, 0, s[4:5]
	v_add_f32_e32 v56, v64, v56
	v_cmp_gt_i32_e64 s[4:5], 15, v80
	s_waitcnt vmcnt(1)
	v_lshlrev_b32_e32 v68, 16, v4
	s_waitcnt vmcnt(0)
	v_lshlrev_b32_e32 v64, 16, v8
	v_and_b32_e32 v8, 0xffff0000, v8
	v_and_b32_e32 v4, 0xffff0000, v4
	v_lshlrev_b32_e32 v65, 16, v9
	v_lshlrev_b32_e32 v69, 16, v5
	v_cndmask_b32_e64 v8, v8, 0, vcc
	v_cndmask_b32_e64 v4, v4, 0, vcc
	v_and_b32_e32 v9, 0xffff0000, v9
	v_and_b32_e32 v5, 0xffff0000, v5
	v_add_f32_e32 v60, v60, v8
	v_cndmask_b32_e64 v8, v65, 0, vcc
	v_add_f32_e32 v49, v49, v4
	v_cndmask_b32_e64 v4, v69, 0, vcc
	v_lshlrev_b32_e32 v66, 16, v10
	v_lshlrev_b32_e32 v70, 16, v6
	v_add_f32_e32 v57, v57, v8
	v_cndmask_b32_e64 v8, v9, 0, vcc
	v_add_f32_e32 v50, v50, v4
	v_cndmask_b32_e64 v4, v5, 0, vcc
	v_and_b32_e32 v10, 0xffff0000, v10
	v_and_b32_e32 v6, 0xffff0000, v6
	v_add_f32_e32 v61, v61, v8
	v_cndmask_b32_e64 v8, v66, 0, vcc
	v_add_f32_e32 v51, v51, v4
	v_cndmask_b32_e64 v4, v70, 0, vcc
	v_lshlrev_b32_e32 v67, 16, v11
	v_lshlrev_b32_e32 v71, 16, v7
	v_add_f32_e32 v58, v58, v8
	v_cndmask_b32_e64 v8, v10, 0, vcc
	v_add_f32_e32 v52, v52, v4
	v_cndmask_b32_e64 v4, v6, 0, vcc
	v_and_b32_e32 v11, 0xffff0000, v11
	v_and_b32_e32 v7, 0xffff0000, v7
	v_add_f32_e32 v62, v62, v8
	v_cndmask_b32_e64 v8, v67, 0, vcc
	v_add_f32_e32 v53, v53, v4
	v_cndmask_b32_e64 v4, v71, 0, vcc
	v_add_f32_e32 v59, v59, v8
	v_cndmask_b32_e64 v8, v11, 0, vcc
	v_add_f32_e32 v54, v54, v4
	v_cndmask_b32_e64 v4, v7, 0, vcc
	v_cndmask_b32_e64 v64, v64, 0, vcc
	v_add_f32_e32 v63, v63, v8
	v_cndmask_b32_e64 v8, v68, 0, vcc
	v_add_f32_e32 v55, v55, v4
	v_cmp_gt_i32_e32 vcc, 8, v80
	v_mov_b32_e32 v4, 0xffff7000
	v_add_f32_e32 v48, v48, v8
	v_cndmask_b32_e64 v5, -1, 0, vcc
	v_cndmask_b32_e64 v4, v4, 0, vcc
	v_lshl_add_u64 v[8:9], v[42:43], 0, v[4:5]
	global_load_dwordx4 v[4:7], v[8:9], off offset:16
	s_nop 0
	global_load_dwordx4 v[8:11], v[8:9], off
	v_add_f32_e32 v56, v56, v64
	s_waitcnt vmcnt(1)
	v_lshlrev_b32_e32 v68, 16, v4
	s_waitcnt vmcnt(0)
	v_lshlrev_b32_e32 v64, 16, v8
	v_and_b32_e32 v8, 0xffff0000, v8
	v_and_b32_e32 v4, 0xffff0000, v4
	v_lshlrev_b32_e32 v65, 16, v9
	v_lshlrev_b32_e32 v69, 16, v5
	v_cndmask_b32_e64 v8, v8, 0, vcc
	v_cndmask_b32_e64 v4, v4, 0, vcc
	v_and_b32_e32 v9, 0xffff0000, v9
	v_and_b32_e32 v5, 0xffff0000, v5
	v_add_f32_e32 v60, v60, v8
	v_cndmask_b32_e64 v8, v65, 0, vcc
	v_add_f32_e32 v49, v49, v4
	v_cndmask_b32_e64 v4, v69, 0, vcc
	v_lshlrev_b32_e32 v66, 16, v10
	v_lshlrev_b32_e32 v70, 16, v6
	v_add_f32_e32 v57, v57, v8
	v_cndmask_b32_e64 v8, v9, 0, vcc
	v_add_f32_e32 v50, v50, v4
	v_cndmask_b32_e64 v4, v5, 0, vcc
	v_and_b32_e32 v10, 0xffff0000, v10
	v_and_b32_e32 v6, 0xffff0000, v6
	v_add_f32_e32 v61, v61, v8
	v_cndmask_b32_e64 v8, v66, 0, vcc
	v_add_f32_e32 v51, v51, v4
	v_cndmask_b32_e64 v4, v70, 0, vcc
	v_lshlrev_b32_e32 v67, 16, v11
	v_lshlrev_b32_e32 v71, 16, v7
	v_add_f32_e32 v58, v58, v8
	v_cndmask_b32_e64 v8, v10, 0, vcc
	v_add_f32_e32 v52, v52, v4
	v_cndmask_b32_e64 v4, v6, 0, vcc
	v_and_b32_e32 v11, 0xffff0000, v11
	v_and_b32_e32 v7, 0xffff0000, v7
	v_add_f32_e32 v62, v62, v8
	v_cndmask_b32_e64 v8, v67, 0, vcc
	v_add_f32_e32 v53, v53, v4
	v_cndmask_b32_e64 v4, v71, 0, vcc
	v_add_f32_e32 v59, v59, v8
	v_cndmask_b32_e64 v8, v11, 0, vcc
	v_add_f32_e32 v54, v54, v4
	v_cndmask_b32_e64 v4, v7, 0, vcc
	v_cndmask_b32_e64 v64, v64, 0, vcc
	v_add_f32_e32 v63, v63, v8
	v_cndmask_b32_e64 v8, v68, 0, vcc
	v_add_f32_e32 v55, v55, v4
	v_cmp_gt_i32_e32 vcc, 9, v80
	v_mov_b32_e32 v4, 0xffff5e00
	v_add_f32_e32 v48, v48, v8
	v_cndmask_b32_e64 v5, -1, 0, vcc
	v_cndmask_b32_e64 v4, v4, 0, vcc
	v_lshl_add_u64 v[8:9], v[42:43], 0, v[4:5]
	global_load_dwordx4 v[4:7], v[8:9], off offset:16
	s_nop 0
	global_load_dwordx4 v[8:11], v[8:9], off
	v_add_f32_e32 v56, v56, v64
	s_waitcnt vmcnt(1)
	v_lshlrev_b32_e32 v68, 16, v4
	s_waitcnt vmcnt(0)
	v_lshlrev_b32_e32 v64, 16, v8
	v_and_b32_e32 v8, 0xffff0000, v8
	v_and_b32_e32 v4, 0xffff0000, v4
	v_lshlrev_b32_e32 v65, 16, v9
	v_lshlrev_b32_e32 v69, 16, v5
	v_cndmask_b32_e64 v8, v8, 0, vcc
	v_cndmask_b32_e64 v4, v4, 0, vcc
	v_and_b32_e32 v9, 0xffff0000, v9
	v_and_b32_e32 v5, 0xffff0000, v5
	v_add_f32_e32 v60, v60, v8
	v_cndmask_b32_e64 v8, v65, 0, vcc
	v_add_f32_e32 v49, v49, v4
	v_cndmask_b32_e64 v4, v69, 0, vcc
	v_lshlrev_b32_e32 v66, 16, v10
	v_lshlrev_b32_e32 v70, 16, v6
	v_add_f32_e32 v57, v57, v8
	v_cndmask_b32_e64 v8, v9, 0, vcc
	v_add_f32_e32 v50, v50, v4
	v_cndmask_b32_e64 v4, v5, 0, vcc
	v_and_b32_e32 v10, 0xffff0000, v10
	v_and_b32_e32 v6, 0xffff0000, v6
	v_add_f32_e32 v61, v61, v8
	v_cndmask_b32_e64 v8, v66, 0, vcc
	v_add_f32_e32 v51, v51, v4
	v_cndmask_b32_e64 v4, v70, 0, vcc
	v_lshlrev_b32_e32 v67, 16, v11
	v_lshlrev_b32_e32 v71, 16, v7
	v_add_f32_e32 v58, v58, v8
	v_cndmask_b32_e64 v8, v10, 0, vcc
	v_add_f32_e32 v52, v52, v4
	v_cndmask_b32_e64 v4, v6, 0, vcc
	v_and_b32_e32 v11, 0xffff0000, v11
	v_and_b32_e32 v7, 0xffff0000, v7
	v_add_f32_e32 v62, v62, v8
	v_cndmask_b32_e64 v8, v67, 0, vcc
	v_add_f32_e32 v53, v53, v4
	v_cndmask_b32_e64 v4, v71, 0, vcc
	v_add_f32_e32 v59, v59, v8
	v_cndmask_b32_e64 v8, v11, 0, vcc
	v_add_f32_e32 v54, v54, v4
	v_cndmask_b32_e64 v4, v7, 0, vcc
	v_cndmask_b32_e64 v64, v64, 0, vcc
	v_add_f32_e32 v63, v63, v8
	v_cndmask_b32_e64 v8, v68, 0, vcc
	v_add_f32_e32 v55, v55, v4
	v_cmp_gt_i32_e32 vcc, 10, v80
	v_mov_b32_e32 v4, 0xffff4c00
	v_add_f32_e32 v48, v48, v8
	v_cndmask_b32_e64 v5, -1, 0, vcc
	v_cndmask_b32_e64 v4, v4, 0, vcc
	v_lshl_add_u64 v[8:9], v[42:43], 0, v[4:5]
	global_load_dwordx4 v[4:7], v[8:9], off offset:16
	s_nop 0
	global_load_dwordx4 v[8:11], v[8:9], off
	v_add_f32_e32 v56, v56, v64
	s_waitcnt vmcnt(1)
	v_lshlrev_b32_e32 v68, 16, v4
	s_waitcnt vmcnt(0)
	v_lshlrev_b32_e32 v64, 16, v8
	v_and_b32_e32 v8, 0xffff0000, v8
	v_and_b32_e32 v4, 0xffff0000, v4
	v_lshlrev_b32_e32 v65, 16, v9
	v_lshlrev_b32_e32 v69, 16, v5
	v_cndmask_b32_e64 v8, v8, 0, vcc
	v_cndmask_b32_e64 v4, v4, 0, vcc
	v_and_b32_e32 v9, 0xffff0000, v9
	v_and_b32_e32 v5, 0xffff0000, v5
	v_add_f32_e32 v60, v60, v8
	v_cndmask_b32_e64 v8, v65, 0, vcc
	v_add_f32_e32 v49, v49, v4
	v_cndmask_b32_e64 v4, v69, 0, vcc
	v_lshlrev_b32_e32 v66, 16, v10
	v_lshlrev_b32_e32 v70, 16, v6
	v_add_f32_e32 v57, v57, v8
	v_cndmask_b32_e64 v8, v9, 0, vcc
	v_add_f32_e32 v50, v50, v4
	v_cndmask_b32_e64 v4, v5, 0, vcc
	v_and_b32_e32 v10, 0xffff0000, v10
	v_and_b32_e32 v6, 0xffff0000, v6
	v_add_f32_e32 v61, v61, v8
	v_cndmask_b32_e64 v8, v66, 0, vcc
	v_add_f32_e32 v51, v51, v4
	v_cndmask_b32_e64 v4, v70, 0, vcc
	v_lshlrev_b32_e32 v67, 16, v11
	v_lshlrev_b32_e32 v71, 16, v7
	v_add_f32_e32 v58, v58, v8
	v_cndmask_b32_e64 v8, v10, 0, vcc
	v_add_f32_e32 v52, v52, v4
	v_cndmask_b32_e64 v4, v6, 0, vcc
	v_and_b32_e32 v11, 0xffff0000, v11
	v_and_b32_e32 v7, 0xffff0000, v7
	v_add_f32_e32 v62, v62, v8
	v_cndmask_b32_e64 v8, v67, 0, vcc
	v_add_f32_e32 v53, v53, v4
	v_cndmask_b32_e64 v4, v71, 0, vcc
	v_add_f32_e32 v59, v59, v8
	v_cndmask_b32_e64 v8, v11, 0, vcc
	v_add_f32_e32 v54, v54, v4
	v_cndmask_b32_e64 v4, v7, 0, vcc
	v_cndmask_b32_e64 v64, v64, 0, vcc
	v_add_f32_e32 v63, v63, v8
	v_cndmask_b32_e64 v8, v68, 0, vcc
	v_add_f32_e32 v55, v55, v4
	v_cmp_gt_i32_e32 vcc, 11, v80
	v_mov_b32_e32 v4, 0xffff3a00
	v_add_f32_e32 v48, v48, v8
	v_cndmask_b32_e64 v5, -1, 0, vcc
	v_cndmask_b32_e64 v4, v4, 0, vcc
	v_lshl_add_u64 v[8:9], v[42:43], 0, v[4:5]
	global_load_dwordx4 v[4:7], v[8:9], off offset:16
	s_nop 0
	global_load_dwordx4 v[8:11], v[8:9], off
	v_add_f32_e32 v56, v56, v64
	s_waitcnt vmcnt(1)
	v_lshlrev_b32_e32 v68, 16, v4
	s_waitcnt vmcnt(0)
	v_lshlrev_b32_e32 v64, 16, v8
	v_and_b32_e32 v8, 0xffff0000, v8
	v_lshlrev_b32_e32 v65, 16, v9
	v_and_b32_e32 v4, 0xffff0000, v4
	v_cndmask_b32_e64 v8, v8, 0, vcc
	v_and_b32_e32 v9, 0xffff0000, v9
	v_lshlrev_b32_e32 v69, 16, v5
	v_add_f32_e32 v60, v60, v8
	v_cndmask_b32_e64 v8, v65, 0, vcc
	v_cndmask_b32_e64 v4, v4, 0, vcc
	v_lshlrev_b32_e32 v66, 16, v10
	v_and_b32_e32 v5, 0xffff0000, v5
	v_add_f32_e32 v57, v57, v8
	v_cndmask_b32_e64 v8, v9, 0, vcc
	v_add_f32_e32 v49, v49, v4
	v_cndmask_b32_e64 v4, v69, 0, vcc
	v_and_b32_e32 v10, 0xffff0000, v10
	v_lshlrev_b32_e32 v70, 16, v6
	v_add_f32_e32 v61, v61, v8
	v_cndmask_b32_e64 v8, v66, 0, vcc
	v_add_f32_e32 v50, v50, v4
	v_cndmask_b32_e64 v4, v5, 0, vcc
	v_lshlrev_b32_e32 v67, 16, v11
	v_and_b32_e32 v6, 0xffff0000, v6
	v_cndmask_b32_e64 v64, v64, 0, vcc
	v_add_f32_e32 v58, v58, v8
	v_cndmask_b32_e64 v8, v10, 0, vcc
	v_add_f32_e32 v51, v51, v4
	v_cndmask_b32_e64 v4, v70, 0, vcc
	v_and_b32_e32 v11, 0xffff0000, v11
	v_lshlrev_b32_e32 v71, 16, v7
	v_add_f32_e32 v56, v56, v64
	v_add_f32_e32 v64, v62, v8
	v_cndmask_b32_e64 v8, v67, 0, vcc
	v_add_f32_e32 v66, v52, v4
	v_cndmask_b32_e64 v4, v6, 0, vcc
	v_and_b32_e32 v7, 0xffff0000, v7
	v_add_f32_e32 v59, v59, v8
	v_cndmask_b32_e64 v8, v11, 0, vcc
	v_add_f32_e32 v67, v53, v4
	v_cndmask_b32_e64 v4, v71, 0, vcc
	v_add_f32_e32 v65, v63, v8
	v_cndmask_b32_e64 v8, v68, 0, vcc
	v_add_f32_e32 v68, v54, v4
	v_cndmask_b32_e64 v4, v7, 0, vcc
	v_add_f32_e32 v69, v55, v4
	v_cmp_gt_i32_e32 vcc, 12, v80
	v_mov_b32_e32 v4, 0xffff2800
	v_add_f32_e32 v48, v48, v8
	v_cndmask_b32_e64 v5, -1, 0, vcc
	v_cndmask_b32_e64 v4, v4, 0, vcc
	v_lshl_add_u64 v[8:9], v[42:43], 0, v[4:5]
	global_load_dwordx4 v[4:7], v[8:9], off offset:16
	s_nop 0
	global_load_dwordx4 v[8:11], v[8:9], off
	s_waitcnt vmcnt(1)
	v_lshlrev_b32_e32 v70, 16, v4
	s_waitcnt vmcnt(0)
	v_lshlrev_b32_e32 v52, 16, v8
	v_and_b32_e32 v8, 0xffff0000, v8
	v_lshlrev_b32_e32 v53, 16, v9
	v_cndmask_b32_e64 v8, v8, 0, vcc
	v_and_b32_e32 v9, 0xffff0000, v9
	v_add_f32_e32 v60, v60, v8
	v_cndmask_b32_e64 v8, v53, 0, vcc
	v_lshlrev_b32_e32 v54, 16, v10
	v_and_b32_e32 v4, 0xffff0000, v4
	v_add_f32_e32 v63, v57, v8
	v_cndmask_b32_e64 v8, v9, 0, vcc
	v_and_b32_e32 v10, 0xffff0000, v10
	v_lshlrev_b32_e32 v71, 16, v5
	v_cndmask_b32_e64 v52, v52, 0, vcc
	v_add_f32_e32 v61, v61, v8
	v_cndmask_b32_e64 v8, v54, 0, vcc
	v_cndmask_b32_e64 v4, v4, 0, vcc
	v_lshlrev_b32_e32 v55, 16, v11
	v_and_b32_e32 v5, 0xffff0000, v5
	v_add_f32_e32 v62, v56, v52
	v_add_f32_e32 v58, v58, v8
	v_cndmask_b32_e64 v8, v10, 0, vcc
	v_add_f32_e32 v52, v49, v4
	v_cndmask_b32_e64 v4, v71, 0, vcc
	v_and_b32_e32 v11, 0xffff0000, v11
	v_lshlrev_b32_e32 v72, 16, v6
	v_add_f32_e32 v56, v64, v8
	v_cndmask_b32_e64 v8, v55, 0, vcc
	v_add_f32_e32 v55, v50, v4
	v_cndmask_b32_e64 v4, v5, 0, vcc
	v_and_b32_e32 v6, 0xffff0000, v6
	v_add_f32_e32 v59, v59, v8
	v_cndmask_b32_e64 v8, v11, 0, vcc
	v_add_f32_e32 v53, v51, v4
	v_cndmask_b32_e64 v4, v72, 0, vcc
	v_lshlrev_b32_e32 v73, 16, v7
	v_add_f32_e32 v57, v65, v8
	v_cndmask_b32_e64 v8, v70, 0, vcc
	v_add_f32_e32 v50, v66, v4
	v_cndmask_b32_e64 v4, v6, 0, vcc
	v_and_b32_e32 v7, 0xffff0000, v7
	v_add_f32_e32 v54, v48, v8
	v_add_f32_e32 v48, v67, v4
	v_cndmask_b32_e64 v4, v73, 0, vcc
	v_add_f32_e32 v51, v68, v4
	v_cndmask_b32_e64 v4, v7, 0, vcc
	v_add_f32_e32 v49, v69, v4
	v_cmp_gt_i32_e32 vcc, 13, v80
	v_mov_b32_e32 v4, 0xffff1600
	s_nop 0
	v_cndmask_b32_e64 v5, -1, 0, vcc
	v_cndmask_b32_e64 v4, v4, 0, vcc
	v_lshl_add_u64 v[8:9], v[42:43], 0, v[4:5]
	global_load_dwordx4 v[4:7], v[8:9], off offset:16
	s_nop 0
	global_load_dwordx4 v[8:11], v[8:9], off
	s_waitcnt vmcnt(1)
	v_lshlrev_b32_e32 v68, 16, v4
	s_waitcnt vmcnt(0)
	v_lshlrev_b32_e32 v64, 16, v8
	v_and_b32_e32 v8, 0xffff0000, v8
	v_lshlrev_b32_e32 v65, 16, v9
	v_and_b32_e32 v9, 0xffff0000, v9
	v_lshlrev_b32_e32 v66, 16, v10
	v_and_b32_e32 v10, 0xffff0000, v10
	v_lshlrev_b32_e32 v67, 16, v11
	v_and_b32_e32 v11, 0xffff0000, v11
	v_and_b32_e32 v4, 0xffff0000, v4
	v_lshlrev_b32_e32 v69, 16, v5
	v_and_b32_e32 v5, 0xffff0000, v5
	v_lshlrev_b32_e32 v81, 16, v6
	v_and_b32_e32 v6, 0xffff0000, v6
	v_lshlrev_b32_e32 v82, 16, v7
	v_and_b32_e32 v7, 0xffff0000, v7
	v_cndmask_b32_e64 v78, v64, 0, vcc
	v_cndmask_b32_e64 v76, v8, 0, vcc
	v_cndmask_b32_e64 v79, v65, 0, vcc
	v_cndmask_b32_e64 v77, v9, 0, vcc
	v_cndmask_b32_e64 v74, v66, 0, vcc
	v_cndmask_b32_e64 v72, v10, 0, vcc
	v_cndmask_b32_e64 v75, v67, 0, vcc
	v_cndmask_b32_e64 v73, v11, 0, vcc
	v_cndmask_b32_e64 v70, v68, 0, vcc
	v_cndmask_b32_e64 v68, v4, 0, vcc
	v_cndmask_b32_e64 v71, v69, 0, vcc
	v_cndmask_b32_e64 v69, v5, 0, vcc
	v_cndmask_b32_e64 v66, v81, 0, vcc
	v_cndmask_b32_e64 v64, v6, 0, vcc
	v_cndmask_b32_e64 v67, v82, 0, vcc
	v_cndmask_b32_e64 v65, v7, 0, vcc
	v_cmp_gt_i32_e32 vcc, 14, v80
	v_mov_b32_e32 v4, 0xffff0400
	v_pk_add_f32 v[54:55], v[54:55], v[70:71]
	v_cndmask_b32_e64 v5, -1, 0, vcc
	v_cndmask_b32_e64 v4, v4, 0, vcc
	v_lshl_add_u64 v[8:9], v[42:43], 0, v[4:5]
	global_load_dwordx4 v[4:7], v[8:9], off offset:16
	s_nop 0
	global_load_dwordx4 v[8:11], v[8:9], off
	v_pk_add_f32 v[52:53], v[52:53], v[68:69]
	v_pk_add_f32 v[50:51], v[50:51], v[66:67]
	v_pk_add_f32 v[48:49], v[48:49], v[64:65]
	s_waitcnt vmcnt(1)
	v_lshlrev_b32_e32 v87, 16, v4
	v_and_b32_e32 v86, 0xffff0000, v4
	v_mov_b32_e32 v4, 0xfffef200
	v_lshlrev_b32_e32 v88, 16, v5
	v_and_b32_e32 v85, 0xffff0000, v5
	v_cndmask_b32_e64 v5, -1, 0, s[4:5]
	v_cndmask_b32_e64 v4, v4, 0, s[4:5]
	s_waitcnt vmcnt(0)
	v_lshlrev_b32_e32 v89, 16, v8
	v_lshlrev_b32_e32 v90, 16, v9
	v_and_b32_e32 v91, 0xffff0000, v9
	v_and_b32_e32 v92, 0xffff0000, v8
	v_lshl_add_u64 v[8:9], v[42:43], 0, v[4:5]
	v_lshlrev_b32_e32 v93, 16, v10
	v_lshlrev_b32_e32 v94, 16, v11
	v_and_b32_e32 v95, 0xffff0000, v11
	v_and_b32_e32 v96, 0xffff0000, v10
	v_lshlrev_b32_e32 v83, 16, v6
	v_lshlrev_b32_e32 v84, 16, v7
	v_and_b32_e32 v81, 0xffff0000, v7
	v_and_b32_e32 v82, 0xffff0000, v6
	global_load_dwordx4 v[4:7], v[8:9], off offset:16
	s_nop 0
	global_load_dwordx4 v[8:11], v[8:9], off
	s_waitcnt vmcnt(1)
	v_lshlrev_b32_e32 v105, 16, v4
	s_waitcnt vmcnt(0)
	v_lshlrev_b32_e32 v97, 16, v8
	v_and_b32_e32 v98, 0xffff0000, v8
	v_lshlrev_b32_e32 v99, 16, v9
	v_and_b32_e32 v100, 0xffff0000, v9
	v_and_b32_e32 v106, 0xffff0000, v4
	v_lshlrev_b32_e32 v107, 16, v5
	v_and_b32_e32 v108, 0xffff0000, v5
	v_pk_add_f32 v[4:5], v[62:63], v[78:79]
	v_cndmask_b32_e64 v9, v90, 0, vcc
	v_cndmask_b32_e64 v8, v89, 0, vcc
	v_lshlrev_b32_e32 v109, 16, v6
	v_and_b32_e32 v110, 0xffff0000, v6
	v_lshlrev_b32_e32 v111, 16, v7
	v_and_b32_e32 v112, 0xffff0000, v7
	v_pk_add_f32 v[6:7], v[60:61], v[76:77]
	v_pk_add_f32 v[4:5], v[4:5], v[8:9]
	v_cndmask_b32_e64 v9, v91, 0, vcc
	v_cndmask_b32_e64 v8, v92, 0, vcc
	v_lshlrev_b32_e32 v101, 16, v10
	v_and_b32_e32 v102, 0xffff0000, v10
	v_lshlrev_b32_e32 v103, 16, v11
	v_and_b32_e32 v104, 0xffff0000, v11
	v_pk_add_f32 v[6:7], v[6:7], v[8:9]
	v_cndmask_b32_e64 v9, v99, 0, s[4:5]
	v_cndmask_b32_e64 v8, v97, 0, s[4:5]
	v_cndmask_b32_e64 v11, v100, 0, s[4:5]
	v_cndmask_b32_e64 v10, v98, 0, s[4:5]
	v_pk_add_f32 v[4:5], v[4:5], v[8:9]
	v_pk_add_f32 v[6:7], v[6:7], v[10:11]
	v_pk_add_f32 v[8:9], v[58:59], v[74:75]
	v_pk_add_f32 v[10:11], v[56:57], v[72:73]
	v_cndmask_b32_e64 v57, v94, 0, vcc
	v_cndmask_b32_e64 v56, v93, 0, vcc
	v_pk_add_f32 v[8:9], v[8:9], v[56:57]
	v_cndmask_b32_e64 v57, v95, 0, vcc
	v_cndmask_b32_e64 v56, v96, 0, vcc
	v_pk_add_f32 v[10:11], v[10:11], v[56:57]
	v_cndmask_b32_e64 v57, v103, 0, s[4:5]
	v_cndmask_b32_e64 v56, v101, 0, s[4:5]
	v_pk_add_f32 v[8:9], v[8:9], v[56:57]
	v_cndmask_b32_e64 v57, v88, 0, vcc
	v_cndmask_b32_e64 v56, v87, 0, vcc
	v_cndmask_b32_e64 v59, v104, 0, s[4:5]
	v_cndmask_b32_e64 v58, v102, 0, s[4:5]
	v_pk_add_f32 v[54:55], v[54:55], v[56:57]
	v_cndmask_b32_e64 v57, v85, 0, vcc
	v_cndmask_b32_e64 v56, v86, 0, vcc
	v_pk_add_f32 v[10:11], v[10:11], v[58:59]
	v_pk_add_f32 v[56:57], v[52:53], v[56:57]
	v_cndmask_b32_e64 v53, v107, 0, s[4:5]
	v_cndmask_b32_e64 v52, v105, 0, s[4:5]
	v_cndmask_b32_e64 v59, v108, 0, s[4:5]
	v_cndmask_b32_e64 v58, v106, 0, s[4:5]
	v_pk_add_f32 v[52:53], v[54:55], v[52:53]
	v_pk_add_f32 v[54:55], v[56:57], v[58:59]
	v_cndmask_b32_e64 v57, v84, 0, vcc
	v_cndmask_b32_e64 v56, v83, 0, vcc
	v_pk_add_f32 v[50:51], v[50:51], v[56:57]
	v_cndmask_b32_e64 v57, v81, 0, vcc
	v_cndmask_b32_e64 v56, v82, 0, vcc
	v_pk_add_f32 v[56:57], v[48:49], v[56:57]
	v_cndmask_b32_e64 v49, v111, 0, s[4:5]
	v_cndmask_b32_e64 v48, v109, 0, s[4:5]
	v_cndmask_b32_e64 v59, v112, 0, s[4:5]
	v_cndmask_b32_e64 v58, v110, 0, s[4:5]
	v_pk_add_f32 v[48:49], v[50:51], v[48:49]
	v_pk_add_f32 v[50:51], v[56:57], v[58:59]
	v_min_i32_e32 v56, 15, v80
